# v41 = v37 + MT2 k-loops: next k-tile fragment ds_reads spread through the MFMA run behind their last consumer (instead of a burst before the barrier)
# baseline (speedup 1.0000x reference)
.LBB0_833:
	v_mfma_f32_32x32x16_bf16 v[48:63], v[176:179], v[188:191], v[48:63]
	s_add_i32 s19, s19, 2
	s_add_u32 s10, s10, 0x100
	s_addc_u32 s11, s11, 0
	s_add_u32 s12, s12, 0x100
	s_addc_u32 s13, s13, 0
	s_and_b64 vcc, exec, s[16:17]
	s_waitcnt lgkmcnt(0)
	v_mfma_f32_32x32x16_bf16 v[16:31], v[176:179], v[196:199], v[16:31]
	s_barrier
	v_mfma_f32_32x32x16_bf16 v[32:47], v[184:187], v[188:191], v[32:47]
	ds_read_b128 v[176:179], v207
	ds_read_b128 v[136:139], v207 offset:4704
	v_mfma_f32_32x32x16_bf16 v[0:15], v[184:187], v[196:199], v[0:15]
	ds_read_b128 v[140:143], v208 offset:23136
	ds_read_b128 v[188:191], v208 offset:23040
	v_mfma_f32_32x32x16_bf16 v[48:63], v[152:155], v[156:159], v[48:63]
	ds_read_b128 v[184:187], v208 offset:18432
	v_mfma_f32_32x32x16_bf16 v[16:31], v[152:155], v[172:175], v[16:31]
	v_mfma_f32_32x32x16_bf16 v[32:47], v[160:163], v[156:159], v[32:47]
	ds_read_b128 v[152:155], v207 offset:64
	v_mfma_f32_32x32x16_bf16 v[0:15], v[160:163], v[172:175], v[0:15]
	ds_read_b128 v[156:159], v207 offset:4640
	v_mfma_f32_32x32x16_bf16 v[48:63], v[164:167], v[180:183], v[48:63]
	ds_read_b128 v[160:163], v207 offset:4672
	ds_read_b128 v[172:175], v208 offset:23104
	v_mfma_f32_32x32x16_bf16 v[16:31], v[164:167], v[192:195], v[16:31]
	v_mfma_f32_32x32x16_bf16 v[32:47], v[168:171], v[180:183], v[32:47]
	ds_read_b128 v[164:167], v208 offset:23072
	v_mfma_f32_32x32x16_bf16 v[0:15], v[168:171], v[192:195], v[0:15]
	ds_read_b128 v[180:183], v207 offset:4608
	v_mfma_f32_32x32x16_bf16 v[48:63], v[148:151], v[144:147], v[48:63]
	ds_read_b128 v[168:171], v208 offset:18496
	v_mfma_f32_32x32x16_bf16 v[16:31], v[148:151], v[132:135], v[16:31]
	v_mfma_f32_32x32x16_bf16 v[32:47], v[128:131], v[144:147], v[32:47]
	ds_read_b128 v[148:151], v208 offset:18464
	v_mfma_f32_32x32x16_bf16 v[0:15], v[128:131], v[132:135], v[0:15]
	ds_read_b128 v[144:147], v207 offset:32
	ds_read_b128 v[128:131], v207 offset:96
	ds_read_b128 v[132:135], v208 offset:18528
	s_waitcnt lgkmcnt(0)
	s_cbranch_vccnz .LBB0_839
	s_branch .Lmt2_rd_0

.Lmt2_rd_0:
	s_cmp_lt_u32 s19, 13
	s_waitcnt lgkmcnt(0)
	s_barrier
	s_waitcnt vmcnt(7)
	ds_write_b128 v206, v[64:67]
	s_waitcnt vmcnt(6)
	ds_write_b128 v206, v[68:71] offset:4608
	s_waitcnt vmcnt(5)
	ds_write_b128 v206, v[72:75] offset:9216
	s_waitcnt vmcnt(4)
	ds_write_b128 v206, v[76:79] offset:13824
	s_waitcnt vmcnt(3)
	ds_write_b128 v206, v[88:91] offset:18432
	s_waitcnt vmcnt(2)
	ds_write_b128 v206, v[96:99] offset:23040
	s_waitcnt vmcnt(1)
	ds_write_b128 v206, v[104:107] offset:27648
	s_waitcnt vmcnt(0)
	ds_write_b128 v206, v[108:111] offset:32256
	s_cbranch_scc0 .LBB0_836
	v_lshl_add_u64 v[72:73], s[12:13], 0, v[200:201]
	v_add_co_u32_e32 v64, vcc, 0x2957000, v72
	v_lshl_add_u64 v[104:105], s[10:11], 0, v[200:201]
	s_nop 0
	v_addc_co_u32_e32 v65, vcc, 0, v73, vcc
	v_add_co_u32_e32 v68, vcc, 0x2967000, v72
	s_nop 1
	v_addc_co_u32_e32 v69, vcc, 0, v73, vcc
	v_add_co_u32_e32 v74, vcc, 0x2977000, v72
	global_load_dwordx4 v[64:67], v[64:65], off offset:2688
	s_nop 0
	global_load_dwordx4 v[68:71], v[68:69], off offset:2688
	v_addc_co_u32_e32 v75, vcc, 0, v73, vcc
	v_add_co_u32_e32 v76, vcc, 0x2987000, v72
	s_nop 1
	v_addc_co_u32_e32 v77, vcc, 0, v73, vcc
	v_add_co_u32_e32 v88, vcc, 0x4c0000, v104
	global_load_dwordx4 v[72:75], v[74:75], off offset:2688
	s_nop 0
	global_load_dwordx4 v[76:79], v[76:77], off offset:2688
	v_addc_co_u32_e32 v89, vcc, 0, v105, vcc
	v_add_co_u32_e32 v96, vcc, 0x4d0000, v104
	s_nop 1
	v_addc_co_u32_e32 v97, vcc, 0, v105, vcc
	v_add_co_u32_e32 v106, vcc, 0x4e0000, v104
	global_load_dwordx4 v[88:91], v[88:89], off offset:384
	s_nop 0
	global_load_dwordx4 v[96:99], v[96:97], off offset:384
	v_addc_co_u32_e32 v107, vcc, 0, v105, vcc
	v_add_co_u32_e32 v108, vcc, 0x4f0000, v104
	s_nop 1
	v_addc_co_u32_e32 v109, vcc, 0, v105, vcc
	global_load_dwordx4 v[104:107], v[106:107], off offset:384
	s_nop 0
	global_load_dwordx4 v[108:111], v[108:109], off offset:384
.LBB0_836:
	v_mfma_f32_32x32x16_bf16 v[48:63], v[176:179], v[184:187], v[48:63]
	s_waitcnt lgkmcnt(0)
	s_barrier
	s_cmp_gt_u32 s19, 13
	s_cselect_b64 s[16:17], -1, 0
	s_and_b64 vcc, exec, s[16:17]
	v_mfma_f32_32x32x16_bf16 v[16:31], v[176:179], v[188:191], v[16:31]
	ds_read_b128 v[196:199], v208 offset:23040
	ds_read_b128 v[192:195], v208 offset:23104
	v_mfma_f32_32x32x16_bf16 v[32:47], v[180:183], v[184:187], v[32:47]
	ds_read_b128 v[176:179], v207
	v_mfma_f32_32x32x16_bf16 v[0:15], v[180:183], v[188:191], v[0:15]
	ds_read_b128 v[184:187], v207 offset:4608
	v_mfma_f32_32x32x16_bf16 v[48:63], v[144:147], v[148:151], v[48:63]
	ds_read_b128 v[188:191], v208 offset:18432
	ds_read_b128 v[180:183], v208 offset:18496
	v_mfma_f32_32x32x16_bf16 v[16:31], v[144:147], v[164:167], v[16:31]
	v_mfma_f32_32x32x16_bf16 v[32:47], v[156:159], v[148:151], v[32:47]
	ds_read_b128 v[144:147], v208 offset:18528
	v_mfma_f32_32x32x16_bf16 v[0:15], v[156:159], v[164:167], v[0:15]
	ds_read_b128 v[148:151], v207 offset:96
	v_mfma_f32_32x32x16_bf16 v[48:63], v[152:155], v[168:171], v[48:63]
	ds_read_b128 v[156:159], v208 offset:18464
	ds_read_b128 v[164:167], v207 offset:64
	v_mfma_f32_32x32x16_bf16 v[16:31], v[152:155], v[172:175], v[16:31]
	v_mfma_f32_32x32x16_bf16 v[32:47], v[160:163], v[168:171], v[32:47]
	ds_read_b128 v[152:155], v207 offset:32
	v_mfma_f32_32x32x16_bf16 v[0:15], v[160:163], v[172:175], v[0:15]
	ds_read_b128 v[168:171], v207 offset:4672
	v_mfma_f32_32x32x16_bf16 v[48:63], v[128:131], v[132:135], v[48:63]
	ds_read_b128 v[160:163], v207 offset:4640
	ds_read_b128 v[172:175], v208 offset:23072
	v_mfma_f32_32x32x16_bf16 v[16:31], v[128:131], v[140:143], v[16:31]
	v_mfma_f32_32x32x16_bf16 v[32:47], v[136:139], v[132:135], v[32:47]
	ds_read_b128 v[128:131], v207 offset:4704
	ds_read_b128 v[132:135], v208 offset:23136
	s_waitcnt lgkmcnt(0)
	s_barrier
	v_mfma_f32_32x32x16_bf16 v[0:15], v[136:139], v[140:143], v[0:15]
	s_cbranch_vccnz .LBB0_833
	s_cmp_gt_u32 s19, 11
	ds_write_b128 v206, v[80:83]
	ds_write_b128 v206, v[84:87] offset:4608
	ds_write_b128 v206, v[92:95] offset:9216
	ds_write_b128 v206, v[100:103] offset:13824
	ds_write_b128 v206, v[112:115] offset:18432
	ds_write_b128 v206, v[116:119] offset:23040
	ds_write_b128 v206, v[120:123] offset:27648
	ds_write_b128 v206, v[124:127] offset:32256
	s_cbranch_scc1 .LBB0_833
	v_lshl_add_u64 v[92:93], s[12:13], 0, v[200:201]
	v_add_co_u32_e32 v80, vcc, 0x2957000, v92
	v_lshl_add_u64 v[120:121], s[10:11], 0, v[200:201]
	s_nop 0
	v_addc_co_u32_e32 v81, vcc, 0, v93, vcc
	v_add_co_u32_e32 v84, vcc, 0x2967000, v92
	s_nop 1
	v_addc_co_u32_e32 v85, vcc, 0, v93, vcc
	v_add_co_u32_e32 v94, vcc, 0x2977000, v92
	global_load_dwordx4 v[80:83], v[80:81], off offset:2816
	s_nop 0
	global_load_dwordx4 v[84:87], v[84:85], off offset:2816
	v_addc_co_u32_e32 v95, vcc, 0, v93, vcc
	v_add_co_u32_e32 v100, vcc, 0x2987000, v92
	s_nop 1
	v_addc_co_u32_e32 v101, vcc, 0, v93, vcc
	v_add_co_u32_e32 v112, vcc, 0x4c0000, v120
	global_load_dwordx4 v[92:95], v[94:95], off offset:2816
	s_nop 0
	global_load_dwordx4 v[100:103], v[100:101], off offset:2816
	v_addc_co_u32_e32 v113, vcc, 0, v121, vcc
	v_add_co_u32_e32 v116, vcc, 0x4d0000, v120
	s_nop 1
	v_addc_co_u32_e32 v117, vcc, 0, v121, vcc
	v_add_co_u32_e32 v122, vcc, 0x4e0000, v120
	global_load_dwordx4 v[112:115], v[112:113], off offset:512
	s_nop 0
	global_load_dwordx4 v[116:119], v[116:117], off offset:512
	v_addc_co_u32_e32 v123, vcc, 0, v121, vcc
	v_add_co_u32_e32 v124, vcc, 0x4f0000, v120
	s_nop 1
	v_addc_co_u32_e32 v125, vcc, 0, v121, vcc
	global_load_dwordx4 v[120:123], v[122:123], off offset:512
	s_nop 0
	global_load_dwordx4 v[124:127], v[124:125], off offset:512
	s_branch .LBB0_833

.Lmt2_rd_1:
	s_cmp_lt_u32 s19, 61
	s_waitcnt lgkmcnt(0)
	s_barrier
	s_waitcnt vmcnt(7)
	ds_write_b128 v206, v[64:67]
	s_waitcnt vmcnt(6)
	ds_write_b128 v206, v[68:71] offset:4608
	s_waitcnt vmcnt(5)
	ds_write_b128 v206, v[72:75] offset:9216
	s_waitcnt vmcnt(4)
	ds_write_b128 v206, v[76:79] offset:13824
	s_waitcnt vmcnt(3)
	ds_write_b128 v206, v[88:91] offset:18432
	s_waitcnt vmcnt(2)
	ds_write_b128 v206, v[96:99] offset:23040
	s_waitcnt vmcnt(1)
	ds_write_b128 v206, v[104:107] offset:27648
	s_waitcnt vmcnt(0)
	ds_write_b128 v206, v[108:111] offset:32256
	s_cbranch_scc0 .LBB0_1069
	v_lshl_add_u64 v[72:73], s[12:13], 0, v[200:201]
	v_add_co_u32_e32 v64, vcc, 0x7157000, v72
	v_lshl_add_u64 v[104:105], s[10:11], 0, v[200:201]
	s_nop 0
	v_addc_co_u32_e32 v65, vcc, 0, v73, vcc
	v_add_co_u32_e32 v68, vcc, 0x7197000, v72
	s_nop 1
	v_addc_co_u32_e32 v69, vcc, 0, v73, vcc
	v_add_co_u32_e32 v74, vcc, 0x71d7000, v72
	global_load_dwordx4 v[64:67], v[64:65], off offset:2688
	s_nop 0
	global_load_dwordx4 v[68:71], v[68:69], off offset:2688
	v_addc_co_u32_e32 v75, vcc, 0, v73, vcc
	v_add_co_u32_e32 v76, vcc, 0x7217000, v72
	s_nop 1
	v_addc_co_u32_e32 v77, vcc, 0, v73, vcc
	v_add_co_u32_e32 v88, vcc, 0xec0000, v104
	global_load_dwordx4 v[72:75], v[74:75], off offset:2688
	s_nop 0
	global_load_dwordx4 v[76:79], v[76:77], off offset:2688
	v_addc_co_u32_e32 v89, vcc, 0, v105, vcc
	v_add_co_u32_e32 v96, vcc, 0xf00000, v104
	s_nop 1
	v_addc_co_u32_e32 v97, vcc, 0, v105, vcc
	v_add_co_u32_e32 v106, vcc, 0xf40000, v104
	global_load_dwordx4 v[88:91], v[88:89], off offset:384
	s_nop 0
	global_load_dwordx4 v[96:99], v[96:97], off offset:384
	v_addc_co_u32_e32 v107, vcc, 0, v105, vcc
	v_add_co_u32_e32 v108, vcc, 0xf80000, v104
	s_nop 1
	v_addc_co_u32_e32 v109, vcc, 0, v105, vcc
	global_load_dwordx4 v[104:107], v[106:107], off offset:384
	s_nop 0
	global_load_dwordx4 v[108:111], v[108:109], off offset:384
.LBB0_1069:
	v_mfma_f32_32x32x16_bf16 v[48:63], v[176:179], v[184:187], v[48:63]
	s_waitcnt lgkmcnt(0)
	s_barrier
	s_cmp_gt_u32 s19, 61
	s_cselect_b64 s[16:17], -1, 0
	s_and_b64 vcc, exec, s[16:17]
	v_mfma_f32_32x32x16_bf16 v[16:31], v[176:179], v[188:191], v[16:31]
	ds_read_b128 v[196:199], v208 offset:23040
	ds_read_b128 v[192:195], v208 offset:23104
	v_mfma_f32_32x32x16_bf16 v[32:47], v[180:183], v[184:187], v[32:47]
	ds_read_b128 v[176:179], v207
	v_mfma_f32_32x32x16_bf16 v[0:15], v[180:183], v[188:191], v[0:15]
	ds_read_b128 v[184:187], v207 offset:4608
	v_mfma_f32_32x32x16_bf16 v[48:63], v[144:147], v[148:151], v[48:63]
	ds_read_b128 v[188:191], v208 offset:18432
	ds_read_b128 v[180:183], v208 offset:18496
	v_mfma_f32_32x32x16_bf16 v[16:31], v[144:147], v[164:167], v[16:31]
	v_mfma_f32_32x32x16_bf16 v[32:47], v[156:159], v[148:151], v[32:47]
	ds_read_b128 v[144:147], v208 offset:18528
	v_mfma_f32_32x32x16_bf16 v[0:15], v[156:159], v[164:167], v[0:15]
	ds_read_b128 v[148:151], v207 offset:96
	v_mfma_f32_32x32x16_bf16 v[48:63], v[152:155], v[168:171], v[48:63]
	ds_read_b128 v[156:159], v208 offset:18464
	ds_read_b128 v[164:167], v207 offset:64
	v_mfma_f32_32x32x16_bf16 v[16:31], v[152:155], v[172:175], v[16:31]
	v_mfma_f32_32x32x16_bf16 v[32:47], v[160:163], v[168:171], v[32:47]
	ds_read_b128 v[152:155], v207 offset:32
	v_mfma_f32_32x32x16_bf16 v[0:15], v[160:163], v[172:175], v[0:15]
	ds_read_b128 v[168:171], v207 offset:4672
	v_mfma_f32_32x32x16_bf16 v[48:63], v[128:131], v[132:135], v[48:63]
	ds_read_b128 v[160:163], v207 offset:4640
	ds_read_b128 v[172:175], v208 offset:23072
	v_mfma_f32_32x32x16_bf16 v[16:31], v[128:131], v[140:143], v[16:31]
	v_mfma_f32_32x32x16_bf16 v[32:47], v[136:139], v[132:135], v[32:47]
	ds_read_b128 v[128:131], v207 offset:4704
	ds_read_b128 v[132:135], v208 offset:23136
	s_waitcnt lgkmcnt(0)
	s_barrier
	v_mfma_f32_32x32x16_bf16 v[0:15], v[136:139], v[140:143], v[0:15]
	s_cbranch_vccnz .LBB0_1066
	s_cmp_gt_u32 s19, 59
	ds_write_b128 v206, v[80:83]
	ds_write_b128 v206, v[84:87] offset:4608
	ds_write_b128 v206, v[92:95] offset:9216
	ds_write_b128 v206, v[100:103] offset:13824
	ds_write_b128 v206, v[112:115] offset:18432
	ds_write_b128 v206, v[116:119] offset:23040
	ds_write_b128 v206, v[120:123] offset:27648
	ds_write_b128 v206, v[124:127] offset:32256
	s_cbranch_scc1 .LBB0_1066
	v_lshl_add_u64 v[92:93], s[12:13], 0, v[200:201]
	v_add_co_u32_e32 v80, vcc, 0x7157000, v92
	v_lshl_add_u64 v[120:121], s[10:11], 0, v[200:201]
	s_nop 0
	v_addc_co_u32_e32 v81, vcc, 0, v93, vcc
	v_add_co_u32_e32 v84, vcc, 0x7197000, v92
	s_nop 1
	v_addc_co_u32_e32 v85, vcc, 0, v93, vcc
	v_add_co_u32_e32 v94, vcc, 0x71d7000, v92
	global_load_dwordx4 v[80:83], v[80:81], off offset:2816
	s_nop 0
	global_load_dwordx4 v[84:87], v[84:85], off offset:2816
	v_addc_co_u32_e32 v95, vcc, 0, v93, vcc
	v_add_co_u32_e32 v100, vcc, 0x7217000, v92
	s_nop 1
	v_addc_co_u32_e32 v101, vcc, 0, v93, vcc
	v_add_co_u32_e32 v112, vcc, 0xec0000, v120
	global_load_dwordx4 v[92:95], v[94:95], off offset:2816
	s_nop 0
	global_load_dwordx4 v[100:103], v[100:101], off offset:2816
	v_addc_co_u32_e32 v113, vcc, 0, v121, vcc
	v_add_co_u32_e32 v116, vcc, 0xf00000, v120
	s_nop 1
	v_addc_co_u32_e32 v117, vcc, 0, v121, vcc
	v_add_co_u32_e32 v122, vcc, 0xf40000, v120
	global_load_dwordx4 v[112:115], v[112:113], off offset:512
	s_nop 0
	global_load_dwordx4 v[116:119], v[116:117], off offset:512
	v_addc_co_u32_e32 v123, vcc, 0, v121, vcc
	v_add_co_u32_e32 v124, vcc, 0xf80000, v120
	s_nop 1
	v_addc_co_u32_e32 v125, vcc, 0, v121, vcc
	global_load_dwordx4 v[120:123], v[122:123], off offset:512
	s_nop 0
	global_load_dwordx4 v[124:127], v[124:125], off offset:512
	s_branch .LBB0_1066

.LBB0_2046:
	v_mfma_f32_32x32x16_bf16 v[48:63], v[176:179], v[188:191], v[48:63]
	s_add_i32 s17, s17, 2
	s_add_u32 s10, s10, 0x100
	s_addc_u32 s11, s11, 0
	s_add_u32 s12, s12, 0x100
	s_addc_u32 s13, s13, 0
	s_and_b64 vcc, exec, s[14:15]
	s_waitcnt lgkmcnt(0)
	v_mfma_f32_32x32x16_bf16 v[16:31], v[176:179], v[196:199], v[16:31]
	s_barrier
	v_mfma_f32_32x32x16_bf16 v[32:47], v[184:187], v[188:191], v[32:47]
	ds_read_b128 v[176:179], v207
	ds_read_b128 v[136:139], v207 offset:4704
	v_mfma_f32_32x32x16_bf16 v[0:15], v[184:187], v[196:199], v[0:15]
	ds_read_b128 v[140:143], v208 offset:23136
	ds_read_b128 v[188:191], v208 offset:23040
	v_mfma_f32_32x32x16_bf16 v[48:63], v[152:155], v[156:159], v[48:63]
	ds_read_b128 v[184:187], v208 offset:18432
	v_mfma_f32_32x32x16_bf16 v[16:31], v[152:155], v[172:175], v[16:31]
	v_mfma_f32_32x32x16_bf16 v[32:47], v[160:163], v[156:159], v[32:47]
	ds_read_b128 v[152:155], v207 offset:64
	v_mfma_f32_32x32x16_bf16 v[0:15], v[160:163], v[172:175], v[0:15]
	ds_read_b128 v[156:159], v207 offset:4640
	v_mfma_f32_32x32x16_bf16 v[48:63], v[164:167], v[180:183], v[48:63]
	ds_read_b128 v[160:163], v207 offset:4672
	ds_read_b128 v[172:175], v208 offset:23104
	v_mfma_f32_32x32x16_bf16 v[16:31], v[164:167], v[192:195], v[16:31]
	v_mfma_f32_32x32x16_bf16 v[32:47], v[168:171], v[180:183], v[32:47]
	ds_read_b128 v[164:167], v208 offset:23072
	v_mfma_f32_32x32x16_bf16 v[0:15], v[168:171], v[192:195], v[0:15]
	ds_read_b128 v[180:183], v207 offset:4608
	v_mfma_f32_32x32x16_bf16 v[48:63], v[148:151], v[144:147], v[48:63]
	ds_read_b128 v[168:171], v208 offset:18496
	v_mfma_f32_32x32x16_bf16 v[16:31], v[148:151], v[132:135], v[16:31]
	v_mfma_f32_32x32x16_bf16 v[32:47], v[128:131], v[144:147], v[32:47]
	ds_read_b128 v[148:151], v208 offset:18464
	v_mfma_f32_32x32x16_bf16 v[0:15], v[128:131], v[132:135], v[0:15]
	ds_read_b128 v[144:147], v207 offset:32
	ds_read_b128 v[128:131], v207 offset:96
	ds_read_b128 v[132:135], v208 offset:18528
	s_waitcnt lgkmcnt(0)
	s_cbranch_vccnz .LBB0_2052
	s_branch .Lmt2_rd_3

.Lmt2_rd_3:
	s_cmp_lt_u32 s17, 61
	s_waitcnt lgkmcnt(0)
	s_barrier
	s_waitcnt vmcnt(7)
	ds_write_b128 v206, v[64:67]
	s_waitcnt vmcnt(6)
	ds_write_b128 v206, v[68:71] offset:4608
	s_waitcnt vmcnt(5)
	ds_write_b128 v206, v[72:75] offset:9216
	s_waitcnt vmcnt(4)
	ds_write_b128 v206, v[76:79] offset:13824
	s_waitcnt vmcnt(3)
	ds_write_b128 v206, v[88:91] offset:18432
	s_waitcnt vmcnt(2)
	ds_write_b128 v206, v[96:99] offset:23040
	s_waitcnt vmcnt(1)
	ds_write_b128 v206, v[104:107] offset:27648
	s_waitcnt vmcnt(0)
	ds_write_b128 v206, v[108:111] offset:32256
	s_cbranch_scc0 .LBB0_2049
	v_lshl_add_u64 v[72:73], s[12:13], 0, v[200:201]
	v_add_co_u32_e32 v64, vcc, 0x7157000, v72
	v_lshl_add_u64 v[104:105], s[10:11], 0, v[200:201]
	s_nop 0
	v_addc_co_u32_e32 v65, vcc, 0, v73, vcc
	v_add_co_u32_e32 v68, vcc, 0x7197000, v72
	s_nop 1
	v_addc_co_u32_e32 v69, vcc, 0, v73, vcc
	v_add_co_u32_e32 v74, vcc, 0x71d7000, v72
	global_load_dwordx4 v[64:67], v[64:65], off offset:2688
	s_nop 0
	global_load_dwordx4 v[68:71], v[68:69], off offset:2688
	v_addc_co_u32_e32 v75, vcc, 0, v73, vcc
	v_add_co_u32_e32 v76, vcc, 0x7217000, v72
	s_nop 1
	v_addc_co_u32_e32 v77, vcc, 0, v73, vcc
	v_add_co_u32_e32 v88, vcc, 0xec0000, v104
	global_load_dwordx4 v[72:75], v[74:75], off offset:2688
	s_nop 0
	global_load_dwordx4 v[76:79], v[76:77], off offset:2688
	v_addc_co_u32_e32 v89, vcc, 0, v105, vcc
	v_add_co_u32_e32 v96, vcc, 0xf00000, v104
	s_nop 1
	v_addc_co_u32_e32 v97, vcc, 0, v105, vcc
	v_add_co_u32_e32 v106, vcc, 0xf40000, v104
	global_load_dwordx4 v[88:91], v[88:89], off offset:384
	s_nop 0
	global_load_dwordx4 v[96:99], v[96:97], off offset:384
	v_addc_co_u32_e32 v107, vcc, 0, v105, vcc
	v_add_co_u32_e32 v108, vcc, 0xf80000, v104
	s_nop 1
	v_addc_co_u32_e32 v109, vcc, 0, v105, vcc
	global_load_dwordx4 v[104:107], v[106:107], off offset:384
	s_nop 0
	global_load_dwordx4 v[108:111], v[108:109], off offset:384
.LBB0_2049:
	v_mfma_f32_32x32x16_bf16 v[48:63], v[176:179], v[184:187], v[48:63]
	s_waitcnt lgkmcnt(0)
	s_barrier
	s_cmp_gt_u32 s17, 61
	s_cselect_b64 s[14:15], -1, 0
	s_and_b64 vcc, exec, s[14:15]
	v_mfma_f32_32x32x16_bf16 v[16:31], v[176:179], v[188:191], v[16:31]
	ds_read_b128 v[196:199], v208 offset:23040
	ds_read_b128 v[192:195], v208 offset:23104
	v_mfma_f32_32x32x16_bf16 v[32:47], v[180:183], v[184:187], v[32:47]
	ds_read_b128 v[176:179], v207
	v_mfma_f32_32x32x16_bf16 v[0:15], v[180:183], v[188:191], v[0:15]
	ds_read_b128 v[184:187], v207 offset:4608
	v_mfma_f32_32x32x16_bf16 v[48:63], v[144:147], v[148:151], v[48:63]
	ds_read_b128 v[188:191], v208 offset:18432
	ds_read_b128 v[180:183], v208 offset:18496
	v_mfma_f32_32x32x16_bf16 v[16:31], v[144:147], v[164:167], v[16:31]
	v_mfma_f32_32x32x16_bf16 v[32:47], v[156:159], v[148:151], v[32:47]
	ds_read_b128 v[144:147], v208 offset:18528
	v_mfma_f32_32x32x16_bf16 v[0:15], v[156:159], v[164:167], v[0:15]
	ds_read_b128 v[148:151], v207 offset:96
	v_mfma_f32_32x32x16_bf16 v[48:63], v[152:155], v[168:171], v[48:63]
	ds_read_b128 v[156:159], v208 offset:18464
	ds_read_b128 v[164:167], v207 offset:64
	v_mfma_f32_32x32x16_bf16 v[16:31], v[152:155], v[172:175], v[16:31]
	v_mfma_f32_32x32x16_bf16 v[32:47], v[160:163], v[168:171], v[32:47]
	ds_read_b128 v[152:155], v207 offset:32
	v_mfma_f32_32x32x16_bf16 v[0:15], v[160:163], v[172:175], v[0:15]
	ds_read_b128 v[168:171], v207 offset:4672
	v_mfma_f32_32x32x16_bf16 v[48:63], v[128:131], v[132:135], v[48:63]
	ds_read_b128 v[160:163], v207 offset:4640
	ds_read_b128 v[172:175], v208 offset:23072
	v_mfma_f32_32x32x16_bf16 v[16:31], v[128:131], v[140:143], v[16:31]
	v_mfma_f32_32x32x16_bf16 v[32:47], v[136:139], v[132:135], v[32:47]
	ds_read_b128 v[128:131], v207 offset:4704
	ds_read_b128 v[132:135], v208 offset:23136
	s_waitcnt lgkmcnt(0)
	s_barrier
	v_mfma_f32_32x32x16_bf16 v[0:15], v[136:139], v[140:143], v[0:15]
	s_cbranch_vccnz .LBB0_2046
	s_cmp_gt_u32 s17, 59
	ds_write_b128 v206, v[80:83]
	ds_write_b128 v206, v[84:87] offset:4608
	ds_write_b128 v206, v[92:95] offset:9216
	ds_write_b128 v206, v[100:103] offset:13824
	ds_write_b128 v206, v[112:115] offset:18432
	ds_write_b128 v206, v[116:119] offset:23040
	ds_write_b128 v206, v[120:123] offset:27648
	ds_write_b128 v206, v[124:127] offset:32256
	s_cbranch_scc1 .LBB0_2046
	v_lshl_add_u64 v[92:93], s[12:13], 0, v[200:201]
	v_add_co_u32_e32 v80, vcc, 0x7157000, v92
	v_lshl_add_u64 v[120:121], s[10:11], 0, v[200:201]
	s_nop 0
	v_addc_co_u32_e32 v81, vcc, 0, v93, vcc
	v_add_co_u32_e32 v84, vcc, 0x7197000, v92
	s_nop 1
	v_addc_co_u32_e32 v85, vcc, 0, v93, vcc
	v_add_co_u32_e32 v94, vcc, 0x71d7000, v92
	global_load_dwordx4 v[80:83], v[80:81], off offset:2816
	s_nop 0
	global_load_dwordx4 v[84:87], v[84:85], off offset:2816
	v_addc_co_u32_e32 v95, vcc, 0, v93, vcc
	v_add_co_u32_e32 v100, vcc, 0x7217000, v92
	s_nop 1
	v_addc_co_u32_e32 v101, vcc, 0, v93, vcc
	v_add_co_u32_e32 v112, vcc, 0xec0000, v120
	global_load_dwordx4 v[92:95], v[94:95], off offset:2816
	s_nop 0
	global_load_dwordx4 v[100:103], v[100:101], off offset:2816
	v_addc_co_u32_e32 v113, vcc, 0, v121, vcc
	v_add_co_u32_e32 v116, vcc, 0xf00000, v120
	s_nop 1
	v_addc_co_u32_e32 v117, vcc, 0, v121, vcc
	v_add_co_u32_e32 v122, vcc, 0xf40000, v120
	global_load_dwordx4 v[112:115], v[112:113], off offset:512
	s_nop 0
	global_load_dwordx4 v[116:119], v[116:117], off offset:512
	v_addc_co_u32_e32 v123, vcc, 0, v121, vcc
	v_add_co_u32_e32 v124, vcc, 0xf80000, v120
	s_nop 1
	v_addc_co_u32_e32 v125, vcc, 0, v121, vcc
	global_load_dwordx4 v[120:123], v[122:123], off offset:512
	s_nop 0
	global_load_dwordx4 v[124:127], v[124:125], off offset:512
	s_branch .LBB0_2046
